# attention K tiles via coalesced LDS-DMA prefetch into swizzled LDS image
# speedup vs baseline: 1.0155x; 1.0014x over previous
.LBB0_1429:
	v_mov_b32_e32 v4, v252
	s_waitcnt vmcnt(63) expcnt(7) lgkmcnt(15)
	v_readfirstlane_b32 s4, v4
	s_barrier
	s_load_dwordx2 s[2:3], s[0:1], 0x40
	s_ashr_i32 s10, s4, 6
	v_and_b32_e32 v173, 63, v4
	s_mul_i32 s6, s10, 0x101
	s_mul_i32 s5, s10, 0x410
	v_add_u32_e32 v2, s6, v173
	s_add_i32 s8, s5, 0
	v_ashrrev_i32_e32 v3, 31, v2
	v_or_b32_e32 v0, 0xffffffc0, v173
	v_lshl_add_u32 v5, v173, 2, s8
	s_waitcnt lgkmcnt(0)
	v_lshl_add_u64 v[2:3], v[2:3], 2, s[2:3]
	s_mov_b64 s[2:3], 0
	global_load_dword v243, v[2:3], off
	global_load_dword v248, v[2:3], off offset:256
	global_load_dword v249, v[2:3], off offset:512
	global_load_dword v250, v[2:3], off offset:768
	v_cmp_eq_u32_e32 vcc, 0xffffffc0, v0
	s_and_saveexec_b64 s[2:3], vcc
	global_load_dword v251, v[2:3], off offset:1024
	s_waitcnt vmcnt(0)
	v_mul_f32_e32 v251, 0x3fb8aa3b, v251
	ds_write_b32 v5, v251 offset:1024
	s_or_b64 exec, exec, s[2:3]
	v_mul_f32_e32 v243, 0x3fb8aa3b, v243
	v_mul_f32_e32 v248, 0x3fb8aa3b, v248
	v_mul_f32_e32 v249, 0x3fb8aa3b, v249
	v_mul_f32_e32 v250, 0x3fb8aa3b, v250
	ds_write_b32 v5, v243
	ds_write_b32 v5, v248 offset:256
	ds_write_b32 v5, v249 offset:512
	ds_write_b32 v5, v250 offset:768
	s_add_i32 s11, s18, 0xffb9
	s_and_b32 s9, s11, 0xffff
	s_mul_i32 s2, s9, 0x8889
	s_lshr_b32 s2, s2, 22
	s_lshl_b32 s3, s2, 7
	s_mulk_i32 s2, 0x78
	s_sub_i32 s2, s11, s2
	s_add_i32 s2, s2, 8
	s_and_b32 s2, s2, 0xffff
	s_add_i32 s33, s3, s2
	s_lshr_b32 s2, s33, 7
	s_lshl_b32 s76, s2, 22
	s_lshl_b32 s2, s2, 3
	s_and_b32 s6, s4, 0xffffffc0
	s_add_i32 s2, s10, s2
	s_ashr_i32 s7, s6, 31
	s_ashr_i32 s3, s2, 31
	s_lshl_b64 s[2:3], s[2:3], 20
	s_lshl_b64 s[4:5], s[6:7], 1
	v_lshrrev_b32_e32 v5, 5, v173
	s_add_u32 s30, s95, s4
	v_and_b32_e32 v172, 31, v4
	s_addc_u32 s31, s22, s5
	v_lshlrev_b32_e32 v0, 4, v5
	v_lshl_add_u64 v[2:3], s[30:31], 0, v[0:1]
	v_lshl_or_b32 v0, s33, 6, v172
	v_lshlrev_b64 v[6:7], 10, v[0:1]
	v_or_b32_e32 v162, 32, v0
	v_mov_b32_e32 v163, v1
	v_lshl_add_u64 v[18:19], v[2:3], 0, v[6:7]
	v_lshlrev_b64 v[6:7], 10, v[162:163]
	s_waitcnt lgkmcnt(0)
	s_barrier
	v_lshl_add_u64 v[2:3], v[2:3], 0, v[6:7]
	global_load_dwordx4 v[6:9], v[18:19], off
	global_load_dwordx4 v[10:13], v[18:19], off offset:32
	global_load_dwordx4 v[14:17], v[18:19], off offset:64
	s_nop 0
	global_load_dwordx4 v[18:21], v[18:19], off offset:96
	s_nop 0
	global_load_dwordx4 v[22:25], v[2:3], off
	global_load_dwordx4 v[26:29], v[2:3], off offset:32
	global_load_dwordx4 v[30:33], v[2:3], off offset:64
	global_load_dwordx4 v[34:37], v[2:3], off offset:96
	s_mulk_i32 s10, 0x1bf0
	v_lshlrev_b32_e32 v38, 4, v173
	s_add_i32 s10, s8, s10
	v_and_b32_e32 v3, 32, v4
	v_add_u32_e32 v174, s10, v38
	s_lshl_b32 s10, s11, 16
	v_lshlrev_b32_e32 v2, 10, v172
	v_lshrrev_b32_e32 v3, 1, v3
	v_or3_b32 v2, s10, v2, v3
	s_lshl_b64 s[10:11], s[76:77], 1
	s_add_u32 s10, s10, s4
	v_mov_b32_e32 v3, v1
	s_addc_u32 s11, s11, s5
	v_lshl_add_u64 v[2:3], s[10:11], 0, v[2:3]
	s_mul_hi_u32 s10, s9, 0x2222223
	s_mul_hi_u32 s11, s10, 0x780000
	s_mul_i32 s30, s10, 0x780000
	v_subrev_co_u32_e32 v166, vcc, s30, v2
	v_mov_b32_e32 v2, s11
	s_lshl_b32 s9, s9, 13
	v_subb_co_u32_e32 v167, vcc, v3, v2, vcc
	s_add_u32 s2, s2, s9
	v_lshlrev_b32_e32 v2, 4, v172
	v_lshlrev_b32_e32 v3, 10, v5
	v_or3_b32 v2, v3, v2, s2
	s_addc_u32 s3, s3, 0
	v_or_b32_e32 v3, 0x200, v2
	s_mul_i32 s10, s10, 0xf0000
	v_mov_b32_e32 v4, s3
	v_subrev_co_u32_e32 v168, vcc, s10, v3
	v_lshlrev_b32_e32 v165, 2, v5
	s_nop 0
	v_subbrev_co_u32_e32 v169, vcc, 0, v4, vcc
	v_subrev_co_u32_e32 v170, vcc, s10, v2
	v_sub_u32_e32 v2, v172, v165
	s_nop 0
	v_subbrev_co_u32_e32 v171, vcc, 0, v4, vcc
	v_add_u32_e32 v177, 0x220, v2
	v_mov_b32_e32 v2, v1
	v_mov_b32_e32 v3, v1
	v_mov_b32_e32 v4, v1
	v_mov_b32_e32 v5, v1
	v_mov_b32_e32 v175, 0
	v_mov_b32_e32 v189, 0xf149f2ca
	s_mov_b32 s9, -1
	v_mov_b32_e32 v199, 0xf149f2ca
	v_mov_b32_e32 v176, 0
	v_readfirstlane_b32 s98, v252
	v_mbcnt_lo_u32_b32 v249, -1, 0
	v_mbcnt_hi_u32_b32 v249, -1, v249
	s_lshr_b32 s101, s98, 6
	s_lshl_b32 s98, s101, 13
	s_add_i32 s98, s98, 0x14000
	s_add_i32 s99, s98, 0x1c00
	s_mov_b32 s100, 0x1000
	s_cmp_eq_u32 s101, 7
	s_cselect_b32 s99, 0x3000, s99
	s_cselect_b32 s100, 0xfffe0400, s100
	v_and_b32_e32 v246, 31, v249
	v_lshrrev_b32_e32 v247, 5, v249
	v_bfe_u32 v248, v249, 1, 3
	v_lshl_add_u32 v250, v246, 7, s98
	v_xor_b32_e32 v241, v247, v248
	v_lshl_add_u32 v241, v241, 4, v250
	v_or_b32_e32 v242, 2, v247
	v_xor_b32_e32 v242, v242, v248
	v_lshl_add_u32 v242, v242, 4, v250
	v_or_b32_e32 v243, 4, v247
	v_xor_b32_e32 v243, v243, v248
	v_lshl_add_u32 v243, v243, 4, v250
	v_or_b32_e32 v244, 6, v247
	v_xor_b32_e32 v244, v244, v248
	v_lshl_add_u32 v244, v244, 4, v250
	v_mov_b32_e32 v245, 0x1000
	v_mov_b32_e32 v251, s100
	v_cmp_lt_u32_e32 vcc, 23, v246
	s_nop 1
	v_cndmask_b32_e32 v245, v245, v251, vcc
	v_add_u32_e32 v248, v244, v245
	v_add_u32_e32 v247, v243, v245
	v_add_u32_e32 v246, v242, v245
	v_add_u32_e32 v245, v241, v245
	v_lshrrev_b32_e32 v250, 3, v249
	v_lshlrev_b32_e32 v250, 10, v250
	v_and_b32_e32 v251, 7, v249
	v_lshrrev_b32_e32 v142, 4, v249
	v_xor_b32_e32 v251, v251, v142
	v_lshl_add_u32 v142, v251, 4, v250
	v_xor_b32_e32 v251, 4, v251
	v_lshl_add_u32 v250, v251, 4, v250
	v_add_u32_e32 v250, 0x2000, v250
	v_readfirstlane_b32 s100, v166
	v_readfirstlane_b32 s101, v167
	s_nop 0
	s_add_u32 s100, s100, s86
	s_addc_u32 s101, s101, s87
	s_add_u32 s100, s100, 0x85ee200
	s_addc_u32 s101, s101, 0
	v_mov_b32_e32 v143, 0
	v_mov_b32_e32 v251, 0
	v_lshl_add_u64 v[166:167], s[100:101], 0, v[142:143]
	v_lshl_add_u64 v[250:251], s[100:101], 0, v[250:251]
	s_mov_b64 s[100:101], 0x4000
	s_mov_b32 m0, s98
	s_nop 0
	global_load_lds_dwordx4 v[166:167], off
	s_add_i32 m0, s98, 0x400
	s_nop 0
	global_load_lds_dwordx4 v[250:251], off
	v_lshl_add_u64 v[142:143], v[166:167], 0, s[100:101]
	s_add_i32 m0, s98, 0x800
	s_nop 0
	global_load_lds_dwordx4 v[142:143], off
	v_lshl_add_u64 v[144:145], v[250:251], 0, s[100:101]
	s_add_i32 m0, s98, 0xc00
	s_nop 0
	global_load_lds_dwordx4 v[144:145], off
	v_lshl_add_u64 v[142:143], v[142:143], 0, s[100:101]
	s_add_i32 m0, s98, 0x1000
	s_nop 0
	global_load_lds_dwordx4 v[142:143], off
	v_lshl_add_u64 v[144:145], v[144:145], 0, s[100:101]
	s_add_i32 m0, s98, 0x1400
	s_nop 0
	global_load_lds_dwordx4 v[144:145], off
	v_lshl_add_u64 v[142:143], v[142:143], 0, s[100:101]
	s_add_i32 m0, s98, 0x1800
	s_nop 0
	global_load_lds_dwordx4 v[142:143], off
	v_lshl_add_u64 v[144:145], v[144:145], 0, s[100:101]
	s_mov_b32 m0, s99
	s_nop 0
	global_load_lds_dwordx4 v[144:145], off
	s_waitcnt vmcnt(7)
	s_waitcnt vmcnt(6)
	s_waitcnt vmcnt(5)
	s_waitcnt vmcnt(4)
	s_waitcnt vmcnt(3)
	s_waitcnt vmcnt(2)
	s_waitcnt vmcnt(1)
	s_waitcnt vmcnt(0)
	ds_write_b128 v174, v[6:9] offset:16384
	ds_write_b128 v174, v[10:13] offset:17408
	ds_write_b128 v174, v[14:17] offset:18432
	ds_write_b128 v174, v[18:21] offset:19456
	ds_write_b128 v174, v[22:25] offset:20480
	ds_write_b128 v174, v[26:29] offset:21504
	ds_write_b128 v174, v[30:33] offset:22528
	ds_write_b128 v174, v[34:37] offset:23552
	v_mov_b32_e32 v16, v1
	v_mov_b32_e32 v17, v1
	v_mov_b32_e32 v6, v1
	v_mov_b32_e32 v7, v1
	v_mov_b32_e32 v8, v1
	v_mov_b32_e32 v9, v1
	v_mov_b32_e32 v10, v1
	v_mov_b32_e32 v11, v1
	v_mov_b32_e32 v12, v1
	v_mov_b32_e32 v13, v1
	v_mov_b32_e32 v14, v1
	v_mov_b32_e32 v15, v1
	v_mov_b64_e32 v[48:49], v[16:17]
	v_mov_b64_e32 v[32:33], v[16:17]
	v_mov_b64_e32 v[64:65], v[16:17]
	v_mov_b64_e32 v[46:47], v[14:15]
	v_mov_b64_e32 v[44:45], v[12:13]
	v_mov_b64_e32 v[42:43], v[10:11]
	v_mov_b64_e32 v[40:41], v[8:9]
	v_mov_b64_e32 v[38:39], v[6:7]
	v_mov_b64_e32 v[36:37], v[4:5]
	v_mov_b64_e32 v[34:35], v[2:3]
	v_mov_b64_e32 v[30:31], v[14:15]
	v_mov_b64_e32 v[28:29], v[12:13]
	v_mov_b64_e32 v[26:27], v[10:11]
	v_mov_b64_e32 v[24:25], v[8:9]
	v_mov_b64_e32 v[22:23], v[6:7]
	v_mov_b64_e32 v[20:21], v[4:5]
	v_mov_b64_e32 v[18:19], v[2:3]
	v_mov_b64_e32 v[62:63], v[14:15]
	v_mov_b64_e32 v[60:61], v[12:13]
	v_mov_b64_e32 v[58:59], v[10:11]
	v_mov_b64_e32 v[56:57], v[8:9]
	v_mov_b64_e32 v[54:55], v[6:7]
	v_mov_b64_e32 v[52:53], v[4:5]
	v_mov_b64_e32 v[50:51], v[2:3]
.LBB0_1432:
	s_add_i32 s9, s9, 1
	s_waitcnt vmcnt(0)
	ds_read_b128 v[66:69], v241
	ds_read_b128 v[82:85], v242
	ds_read_b128 v[86:89], v243
	ds_read_b128 v[90:93], v244
	ds_read_b128 v[94:97], v245
	ds_read_b128 v[130:133], v246
	ds_read_b128 v[134:137], v247
	ds_read_b128 v[138:141], v248
	ds_read_b128 v[114:117], v174 offset:16384
	ds_read_b128 v[142:145], v174 offset:17408
	ds_read_b128 v[154:157], v174 offset:20480
	ds_read_b128 v[158:161], v174 offset:21504
	s_waitcnt lgkmcnt(3)
	v_mfma_f32_32x32x16_bf16 v[98:113], v[66:69], v[114:117], 0
	ds_read_b128 v[146:149], v174 offset:18432
	ds_read_b128 v[150:153], v174 offset:19456
	ds_read_b128 v[190:193], v174 offset:22528
	ds_read_b128 v[194:197], v174 offset:23552
	s_waitcnt lgkmcnt(5)
	v_mfma_f32_32x32x16_bf16 v[66:81], v[66:69], v[154:157], 0
	v_mfma_f32_32x32x16_bf16 v[98:113], v[82:85], v[142:145], v[98:113]
	s_waitcnt lgkmcnt(4)
	v_mfma_f32_32x32x16_bf16 v[66:81], v[82:85], v[158:161], v[66:81]
	s_waitcnt lgkmcnt(3)
	v_mfma_f32_32x32x16_bf16 v[98:113], v[86:89], v[146:149], v[98:113]
	s_waitcnt lgkmcnt(1)
	v_mfma_f32_32x32x16_bf16 v[66:81], v[86:89], v[190:193], v[66:81]
	v_mfma_f32_32x32x16_bf16 v[98:113], v[90:93], v[150:153], v[98:113]
	s_waitcnt lgkmcnt(0)
	v_mfma_f32_32x32x16_bf16 v[66:81], v[90:93], v[194:197], v[66:81]
	v_mfma_f32_32x32x16_bf16 v[114:129], v[94:97], v[114:117], 0
	v_mfma_f32_32x32x16_bf16 v[82:97], v[94:97], v[154:157], 0
	v_mfma_f32_32x32x16_bf16 v[114:129], v[130:133], v[142:145], v[114:129]
	v_mfma_f32_32x32x16_bf16 v[82:97], v[130:133], v[158:161], v[82:97]
	v_mfma_f32_32x32x16_bf16 v[114:129], v[134:137], v[146:149], v[114:129]
	v_mfma_f32_32x32x16_bf16 v[82:97], v[134:137], v[190:193], v[82:97]
	v_mfma_f32_32x32x16_bf16 v[114:129], v[138:141], v[150:153], v[114:129]
	v_mfma_f32_32x32x16_bf16 v[82:97], v[138:141], v[194:197], v[82:97]
	s_cmp_eq_u32 s9, 8
	s_cbranch_scc1 .Lattn_nopf
	v_lshl_add_u64 v[166:167], v[166:167], 0, s[34:35]
	v_lshl_add_u64 v[250:251], v[250:251], 0, s[34:35]
	s_mov_b32 m0, s98
	s_nop 0
	global_load_lds_dwordx4 v[166:167], off
	s_add_i32 m0, s98, 0x400
	s_nop 0
	global_load_lds_dwordx4 v[250:251], off
	v_lshl_add_u64 v[142:143], v[166:167], 0, s[100:101]
	s_add_i32 m0, s98, 0x800
	s_nop 0
	global_load_lds_dwordx4 v[142:143], off
	v_lshl_add_u64 v[144:145], v[250:251], 0, s[100:101]
	s_add_i32 m0, s98, 0xc00
	s_nop 0
	global_load_lds_dwordx4 v[144:145], off
	v_lshl_add_u64 v[142:143], v[142:143], 0, s[100:101]
	s_add_i32 m0, s98, 0x1000
	s_nop 0
	global_load_lds_dwordx4 v[142:143], off
	v_lshl_add_u64 v[144:145], v[144:145], 0, s[100:101]
	s_add_i32 m0, s98, 0x1400
	s_nop 0
	global_load_lds_dwordx4 v[144:145], off
	v_lshl_add_u64 v[142:143], v[142:143], 0, s[100:101]
	s_add_i32 m0, s98, 0x1800
	s_nop 0
	global_load_lds_dwordx4 v[142:143], off
	v_lshl_add_u64 v[144:145], v[144:145], 0, s[100:101]
	s_mov_b32 m0, s99
	s_nop 0
	global_load_lds_dwordx4 v[144:145], off
.Lattn_nopf:
	v_lshl_add_u64 v[130:131], s[86:87], 0, v[170:171]
	v_add_co_u32_e32 v132, vcc, s88, v130
	s_nop 1
	v_addc_co_u32_e32 v133, vcc, 0, v131, vcc
	v_add_co_u32_e32 v130, vcc, s17, v130
	global_load_dwordx4 v[158:161], v[132:133], off offset:512
	global_load_dwordx4 v[154:157], v[132:133], off offset:1024
	global_load_dwordx4 v[150:153], v[132:133], off offset:2560
	global_load_dwordx4 v[146:149], v[132:133], off offset:3072
	v_addc_co_u32_e32 v131, vcc, 0, v131, vcc
	v_lshl_add_u64 v[132:133], s[86:87], 0, v[168:169]
	v_add_co_u32_e32 v132, vcc, 0xae6f000, v132
	s_nop 1
	v_addc_co_u32_e32 v133, vcc, 0, v133, vcc
	global_load_dwordx4 v[138:141], v[130:131], off offset:512
	global_load_dwordx4 v[134:137], v[130:131], off offset:2560
	global_load_dwordx4 v[142:145], v[132:133], off offset:512
	s_nop 0
	global_load_dwordx4 v[130:133], v[132:133], off offset:2560
	v_mov_b32_e32 v188, s8
	ds_read_b32 v190, v188 offset:1024
	s_cmp_gt_u32 s9, 5
	v_subrev_u32_e32 v188, 32, v177
	s_cselect_b64 s[2:3], -1, 0
	s_cmp_lt_u32 s9, 6
	v_min_i32_e32 v191, 0x80, v188
	s_waitcnt lgkmcnt(0)
	v_mov_b32_e32 v201, v190
	s_cbranch_scc1 .LBB0_1434
	v_lshl_add_u32 v188, v191, 2, s8
	ds_read_b32 v201, v188 offset:512

.LBB0_1517:
	v_cvt_pk_bf16_f32 v126, v125, v126
	v_cvt_pk_bf16_f32 v127, v127, v128
	v_cvt_pk_bf16_f32 v128, v129, v199
	v_cvt_pk_bf16_f32 v129, v201, v204
	v_cvt_pk_bf16_f32 v94, v93, v94
	v_cvt_pk_bf16_f32 v95, v95, v96
	v_cvt_pk_bf16_f32 v96, v97, v189
	v_cvt_pk_bf16_f32 v97, v206, v207
	s_waitcnt vmcnt(7)
	v_mfma_f32_32x32x16_bf16 v[50:65], v[158:161], v[126:129], v[50:65]
	v_cvt_pk_bf16_f32 v76, v76, v77
	v_cvt_pk_bf16_f32 v77, v78, v79
	v_cvt_pk_bf16_f32 v78, v80, v81
	v_cvt_pk_bf16_f32 v79, v82, v83
	v_cvt_pk_bf16_f32 v68, v68, v69
	v_cvt_pk_bf16_f32 v69, v70, v71
	v_cvt_pk_bf16_f32 v70, v72, v73
	v_mfma_f32_32x32x16_bf16 v[18:33], v[158:161], v[94:97], v[18:33]
	v_cvt_pk_bf16_f32 v71, v74, v75
	s_waitcnt lgkmcnt(0)
	v_add_f32_e32 v86, v86, v177
	v_fmac_f32_e32 v86, v175, v66
	v_add_f32_e32 v66, v210, v211
	v_fmac_f32_e32 v66, v176, v98
	v_lshl_add_u64 v[168:169], v[168:169], 0, s[84:85]
	s_waitcnt vmcnt(6)
	v_mfma_f32_32x32x16_bf16 v[34:49], v[154:157], v[126:129], v[34:49]
	v_lshl_add_u64 v[170:171], v[170:171], 0, s[84:85]
	s_cmp_gt_u32 s9, 7
	v_mfma_f32_32x32x16_bf16 v[2:17], v[154:157], v[94:97], v[2:17]
	v_cvt_pk_bf16_f32 v94, v117, v118
	v_cvt_pk_bf16_f32 v95, v119, v120
	v_cvt_pk_bf16_f32 v96, v121, v122
	v_cvt_pk_bf16_f32 v97, v123, v124
	v_cvt_pk_bf16_f32 v118, v84, v85
	v_cvt_pk_bf16_f32 v119, v87, v88
	v_cvt_pk_bf16_f32 v120, v89, v90
	v_cvt_pk_bf16_f32 v121, v91, v92
	s_waitcnt vmcnt(5)
	v_mfma_f32_32x32x16_bf16 v[50:65], v[150:153], v[94:97], v[50:65]
	v_cvt_pk_bf16_f32 v88, v109, v110
	v_cvt_pk_bf16_f32 v89, v111, v112
	v_cvt_pk_bf16_f32 v90, v113, v114
	v_cvt_pk_bf16_f32 v91, v115, v116
	v_mfma_f32_32x32x16_bf16 v[18:33], v[150:153], v[118:121], v[18:33]
	s_waitcnt vmcnt(4)
	v_mfma_f32_32x32x16_bf16 v[34:49], v[146:149], v[94:97], v[34:49]
	v_mfma_f32_32x32x16_bf16 v[2:17], v[146:149], v[118:121], v[2:17]
	s_waitcnt vmcnt(3)
	v_mfma_f32_32x32x16_bf16 v[50:65], v[138:141], v[88:91], v[50:65]
	v_mfma_f32_32x32x16_bf16 v[18:33], v[138:141], v[76:79], v[18:33]
	s_waitcnt vmcnt(1)
	v_mfma_f32_32x32x16_bf16 v[34:49], v[142:145], v[88:91], v[34:49]
	v_mfma_f32_32x32x16_bf16 v[2:17], v[142:145], v[76:79], v[2:17]
	v_cvt_pk_bf16_f32 v76, v101, v102
	v_cvt_pk_bf16_f32 v77, v103, v104
	v_cvt_pk_bf16_f32 v78, v105, v106
	v_cvt_pk_bf16_f32 v79, v107, v108
	s_nop 1
	v_mfma_f32_32x32x16_bf16 v[50:65], v[134:137], v[76:79], v[50:65]
	v_mfma_f32_32x32x16_bf16 v[18:33], v[134:137], v[68:71], v[18:33]
	s_waitcnt vmcnt(0)
	v_mfma_f32_32x32x16_bf16 v[34:49], v[130:133], v[76:79], v[34:49]
	v_mfma_f32_32x32x16_bf16 v[2:17], v[130:133], v[68:71], v[2:17]
	s_cbranch_scc1 .LBB0_1566
	v_mov_b32_e32 v177, v188
	v_mov_b32_e32 v189, v67
	v_mov_b32_e32 v199, v100
	v_mov_b32_e32 v175, v86
	v_mov_b32_e32 v176, v66
	s_branch .LBB0_1432
